# P1 epilogue: RoPE table rows prefetched one row pair ahead into dead fragment VGPRs, counted vmcnt instead of vmcnt(0) per block
# speedup vs baseline: 1.0036x; 1.0036x over previous
.LBB0_167:
	s_or_b64 exec, exec, s[0:1]
	s_lshl_b32 s43, s10, 8
	v_add_u32_e32 v160, s43, v165
	v_and_b32_e32 v144, 0xfcf, v160
	v_cmp_lt_i32_e32 vcc, s78, v160
	v_cmp_gt_i32_e64 s[10:11], s64, v160
	s_nop 0
	v_cndmask_b32_e32 v144, v144, v146, vcc
	v_lshlrev_b32_e32 v144, 6, v144
	v_cmp_gt_i32_e32 vcc, s71, v158
	v_lshl_add_u64 v[162:163], s[40:41], 0, v[144:145]
	s_and_b64 s[52:53], s[4:5], vcc
	s_and_saveexec_b64 s[0:1], s[52:53]
	s_cbranch_execz .LBB0_169
	v_mov_b64_e32 v[202:203], v[162:163]
	v_mov_b32_e32 v228, 0x2000
	v_mov_b32_e32 v229, 0
	v_lshl_add_u64 v[184:185], v[202:203], 0, v[228:229]
	s_lshr_b32 s98, s8, 1
	global_load_dwordx4 v[216:219], v[202:203], off offset:48
	global_load_dwordx4 v[212:215], v[202:203], off offset:32
	global_load_dwordx4 v[208:211], v[202:203], off offset:16
	global_load_dwordx4 v[204:207], v[202:203], off
	global_load_dwordx4 v[236:239], v[202:203], off offset:1072
	global_load_dwordx4 v[232:235], v[202:203], off offset:1056
	global_load_dwordx4 v[224:227], v[202:203], off offset:1040
	global_load_dwordx4 v[220:223], v[202:203], off offset:1024
	s_waitcnt lgkmcnt(0)
	v_mul_f32_e32 v183, v148, v135
	v_mov_b32_e32 v182, v127
	v_mul_f32_e32 v134, v148, v134
	v_pk_mul_f32 v[132:133], v[148:149], v[132:133]
	v_pk_mul_f32 v[128:129], v[148:149], v[128:129]
	v_mul_f32_e32 v130, v148, v130
	s_waitcnt vmcnt(4)
	v_mov_b64_e32 v[186:187], v[216:217]
	v_mov_b64_e32 v[188:189], v[218:219]
	v_mov_b64_e32 v[190:191], v[212:213]
	v_mov_b64_e32 v[192:193], v[214:215]
	v_mov_b64_e32 v[194:195], v[208:209]
	v_mov_b64_e32 v[196:197], v[210:211]
	v_mov_b64_e32 v[198:199], v[204:205]
	v_mov_b64_e32 v[200:201], v[206:207]
	v_mul_f32_e32 v122, v122, v186
	v_mul_f32_e32 v130, v130, v187
	v_pk_mul_f32 v[182:183], v[182:183], v[196:197]
	v_mov_b32_e32 v177, v200
	v_mov_b32_e32 v200, v199
	v_mul_f32_e32 v126, v126, v194
	v_mul_f32_e32 v134, v134, v195
	v_mov_b32_e32 v127, v182
	v_mov_b32_e32 v135, v183
	v_mov_b32_e32 v176, v198
	v_pk_mul_f32 v[132:133], v[132:133], v[200:201]
	v_pk_add_f32 v[126:127], v[126:127], v[134:135]
	v_mul_f32_e32 v135, v148, v131
	v_mov_b32_e32 v134, v123
	v_pk_fma_f32 v[124:125], v[124:125], v[176:177], v[132:133]
	v_mov_b32_e32 v133, v192
	v_mov_b32_e32 v192, v191
	v_pk_mul_f32 v[134:135], v[134:135], v[188:189]
	v_mov_b32_e32 v132, v190
	v_pk_mul_f32 v[128:129], v[128:129], v[192:193]
	v_mov_b32_e32 v123, v134
	v_mov_b32_e32 v131, v135
	v_pk_fma_f32 v[120:121], v[120:121], v[132:133], v[128:129]
	v_pk_add_f32 v[122:123], v[122:123], v[130:131]

.LBB0_177:
	s_or_b64 exec, exec, s[0:1]
	s_movk_i32 s0, 0x380
	v_cmp_gt_i32_e32 vcc, s0, v158
	s_and_b64 s[0:1], s[4:5], vcc
	s_and_saveexec_b64 s[8:9], s[0:1]
	s_cbranch_execz .LBB0_179
	s_waitcnt lgkmcnt(0)
	v_mul_f32_e32 v177, v148, v127
	v_mov_b32_e32 v176, v119
	v_mul_f32_e32 v126, v148, v126
	v_pk_mul_f32 v[124:125], v[148:149], v[124:125]
	v_pk_mul_f32 v[120:121], v[148:149], v[120:121]
	v_mul_f32_e32 v122, v148, v122
	v_mov_b64_e32 v[186:187], v[216:217]
	v_mov_b64_e32 v[188:189], v[218:219]
	v_mov_b64_e32 v[190:191], v[212:213]
	v_mov_b64_e32 v[192:193], v[214:215]
	v_mov_b64_e32 v[194:195], v[208:209]
	v_mov_b64_e32 v[196:197], v[210:211]
	v_mov_b64_e32 v[198:199], v[204:205]
	v_mov_b64_e32 v[200:201], v[206:207]
	v_mul_f32_e32 v114, v114, v186
	v_mul_f32_e32 v122, v122, v187
	v_pk_mul_f32 v[176:177], v[176:177], v[196:197]
	v_mov_b32_e32 v163, v200
	v_mov_b32_e32 v200, v199
	v_mul_f32_e32 v118, v118, v194
	v_mul_f32_e32 v126, v126, v195
	v_mov_b32_e32 v119, v176
	v_mov_b32_e32 v127, v177
	v_mov_b32_e32 v162, v198
	v_pk_mul_f32 v[124:125], v[124:125], v[200:201]
	v_pk_add_f32 v[118:119], v[118:119], v[126:127]
	v_mul_f32_e32 v127, v148, v123
	v_mov_b32_e32 v126, v115
	v_pk_fma_f32 v[116:117], v[116:117], v[162:163], v[124:125]
	v_mov_b32_e32 v125, v192
	v_mov_b32_e32 v192, v191
	v_pk_mul_f32 v[126:127], v[126:127], v[188:189]
	v_mov_b32_e32 v124, v190
	v_pk_mul_f32 v[120:121], v[120:121], v[192:193]
	v_mov_b32_e32 v115, v126
	v_mov_b32_e32 v123, v127
	v_pk_fma_f32 v[112:113], v[112:113], v[124:125], v[120:121]
	v_pk_add_f32 v[114:115], v[114:115], v[122:123]

.LBB0_187:
	s_or_b64 exec, exec, s[10:11]
	v_bitop3_b32 v120, v160, s95, 16 bitop3:0xc8
	v_cmp_lt_i32_e32 vcc, s94, v160
	v_cmp_gt_i32_e64 s[10:11], s93, v160
	s_nop 0
	v_cndmask_b32_e32 v120, v120, v146, vcc
	v_lshlrev_b32_e32 v144, 6, v120
	v_lshl_add_u64 v[120:121], s[40:41], 0, v[144:145]
	s_and_saveexec_b64 s[58:59], s[52:53]
	s_cbranch_execz .LBB0_189
	global_load_dwordx4 v[216:219], v[202:203], off offset:2096
	global_load_dwordx4 v[212:215], v[202:203], off offset:2080
	global_load_dwordx4 v[208:211], v[202:203], off offset:2064
	global_load_dwordx4 v[204:207], v[202:203], off offset:2048
	s_waitcnt lgkmcnt(0)
	v_mul_f32_e32 v118, v148, v118
	v_pk_mul_f32 v[116:117], v[148:149], v[116:117]
	v_pk_mul_f32 v[112:113], v[148:149], v[112:113]
	v_mul_f32_e32 v114, v148, v114
	s_cmp_eq_u32 s98, 0
	s_cbranch_scc1 .Lrp1_q1
	s_waitcnt vmcnt(10)
	s_branch .Lrp1_j1
.Lrp1_q1:
	s_waitcnt vmcnt(6)
.Lrp1_j1:
	v_mov_b64_e32 v[124:125], v[236:237]
	v_mov_b64_e32 v[126:127], v[238:239]
	v_mov_b64_e32 v[128:129], v[232:233]
	v_mov_b64_e32 v[130:131], v[234:235]
	v_mov_b64_e32 v[132:133], v[224:225]
	v_mov_b64_e32 v[134:135], v[226:227]
	v_mov_b64_e32 v[186:187], v[220:221]
	v_mov_b64_e32 v[188:189], v[222:223]
	v_mul_f32_e32 v106, v106, v124
	v_mul_f32_e32 v114, v114, v125
	v_mul_f32_e32 v110, v110, v132
	v_mul_f32_e32 v118, v118, v133
	v_mul_f32_e32 v133, v148, v119
	v_mov_b32_e32 v132, v111
	v_pk_mul_f32 v[132:133], v[132:133], v[134:135]
	v_mov_b32_e32 v163, v188
	v_mov_b32_e32 v188, v187
	v_mov_b32_e32 v111, v132
	v_mov_b32_e32 v119, v133
	v_mov_b32_e32 v162, v186
	v_pk_mul_f32 v[116:117], v[116:117], v[188:189]
	v_pk_add_f32 v[110:111], v[110:111], v[118:119]
	v_mul_f32_e32 v119, v148, v115
	v_mov_b32_e32 v118, v107
	v_pk_fma_f32 v[108:109], v[108:109], v[162:163], v[116:117]
	v_mov_b32_e32 v117, v130
	v_mov_b32_e32 v130, v129
	v_pk_mul_f32 v[118:119], v[118:119], v[126:127]
	v_mov_b32_e32 v116, v128
	v_pk_mul_f32 v[112:113], v[112:113], v[130:131]
	v_mov_b32_e32 v107, v118
	v_mov_b32_e32 v115, v119
	v_pk_fma_f32 v[104:105], v[104:105], v[116:117], v[112:113]
	v_pk_add_f32 v[106:107], v[106:107], v[114:115]

.LBB0_197:
	s_or_b64 exec, exec, s[58:59]
	s_and_saveexec_b64 s[58:59], s[0:1]
	s_cbranch_execz .LBB0_199
	s_waitcnt lgkmcnt(0)
	v_mul_f32_e32 v110, v148, v110
	v_pk_mul_f32 v[108:109], v[148:149], v[108:109]
	v_pk_mul_f32 v[104:105], v[148:149], v[104:105]
	v_mul_f32_e32 v106, v148, v106
	v_mov_b64_e32 v[124:125], v[236:237]
	v_mov_b64_e32 v[126:127], v[238:239]
	v_mov_b64_e32 v[128:129], v[232:233]
	v_mov_b64_e32 v[130:131], v[234:235]
	v_mov_b64_e32 v[132:133], v[224:225]
	v_mov_b64_e32 v[134:135], v[226:227]
	v_mov_b64_e32 v[186:187], v[220:221]
	v_mov_b64_e32 v[188:189], v[222:223]
	v_mul_f32_e32 v98, v98, v124
	v_mul_f32_e32 v106, v106, v125
	v_mul_f32_e32 v102, v102, v132
	v_mul_f32_e32 v110, v110, v133
	v_mul_f32_e32 v133, v148, v111
	v_mov_b32_e32 v132, v103
	v_pk_mul_f32 v[132:133], v[132:133], v[134:135]
	v_mov_b32_e32 v121, v188
	v_mov_b32_e32 v188, v187
	v_mov_b32_e32 v103, v132
	v_mov_b32_e32 v111, v133
	v_mov_b32_e32 v120, v186
	v_pk_mul_f32 v[108:109], v[108:109], v[188:189]
	v_pk_add_f32 v[102:103], v[102:103], v[110:111]
	v_mul_f32_e32 v111, v148, v107
	v_mov_b32_e32 v110, v99
	v_pk_fma_f32 v[100:101], v[100:101], v[120:121], v[108:109]
	v_mov_b32_e32 v109, v130
	v_mov_b32_e32 v130, v129
	v_pk_mul_f32 v[110:111], v[110:111], v[126:127]
	v_mov_b32_e32 v108, v128
	v_pk_mul_f32 v[104:105], v[104:105], v[130:131]
	v_mov_b32_e32 v99, v110
	v_mov_b32_e32 v107, v111
	v_pk_fma_f32 v[96:97], v[96:97], v[108:109], v[104:105]
	v_pk_add_f32 v[98:99], v[98:99], v[106:107]

.LBB0_207:
	s_or_b64 exec, exec, s[10:11]
	v_add_u32_e32 v104, s43, v168
	v_and_b32_e32 v105, 0xfef, v104
	v_cmp_lt_i32_e32 vcc, s78, v104
	v_cmp_gt_i32_e64 s[10:11], s64, v104
	s_nop 0
	v_cndmask_b32_e32 v105, v105, v146, vcc
	v_lshlrev_b32_e32 v144, 6, v105
	v_lshl_add_u64 v[106:107], s[40:41], 0, v[144:145]
	s_and_saveexec_b64 s[58:59], s[52:53]
	s_cbranch_execz .LBB0_209
	global_load_dwordx4 v[236:239], v[202:203], off offset:3120
	global_load_dwordx4 v[232:235], v[202:203], off offset:3104
	global_load_dwordx4 v[224:227], v[202:203], off offset:3088
	global_load_dwordx4 v[220:223], v[202:203], off offset:3072
	s_waitcnt lgkmcnt(0)
	v_mul_f32_e32 v102, v148, v102
	v_pk_mul_f32 v[100:101], v[148:149], v[100:101]
	v_pk_mul_f32 v[96:97], v[148:149], v[96:97]
	v_mul_f32_e32 v98, v148, v98
	s_cmp_eq_u32 s98, 0
	s_cbranch_scc1 .Lrp1_q2
	s_waitcnt vmcnt(10)
	s_branch .Lrp1_j2

.Lrp1_j2:
	v_mov_b64_e32 v[108:109], v[216:217]
	v_mov_b64_e32 v[110:111], v[218:219]
	v_mov_b64_e32 v[112:113], v[212:213]
	v_mov_b64_e32 v[114:115], v[214:215]
	v_mov_b64_e32 v[116:117], v[208:209]
	v_mov_b64_e32 v[118:119], v[210:211]
	v_mov_b64_e32 v[124:125], v[204:205]
	v_mov_b64_e32 v[126:127], v[206:207]
	v_mul_f32_e32 v90, v90, v108
	v_mul_f32_e32 v98, v98, v109
	v_mul_f32_e32 v94, v94, v116
	v_mul_f32_e32 v102, v102, v117
	v_mul_f32_e32 v117, v148, v103
	v_mov_b32_e32 v116, v95
	v_pk_mul_f32 v[116:117], v[116:117], v[118:119]
	v_mov_b32_e32 v121, v126
	v_mov_b32_e32 v126, v125
	v_mov_b32_e32 v95, v116
	v_mov_b32_e32 v103, v117
	v_mov_b32_e32 v120, v124
	v_pk_mul_f32 v[100:101], v[100:101], v[126:127]
	v_pk_add_f32 v[94:95], v[94:95], v[102:103]
	v_mul_f32_e32 v103, v148, v99
	v_mov_b32_e32 v102, v91
	v_pk_fma_f32 v[92:93], v[92:93], v[120:121], v[100:101]
	v_mov_b32_e32 v101, v114
	v_mov_b32_e32 v114, v113
	v_pk_mul_f32 v[102:103], v[102:103], v[110:111]
	v_mov_b32_e32 v100, v112
	v_pk_mul_f32 v[96:97], v[96:97], v[114:115]
	v_mov_b32_e32 v91, v102
	v_mov_b32_e32 v99, v103
	v_pk_fma_f32 v[88:89], v[88:89], v[100:101], v[96:97]
	v_pk_add_f32 v[90:91], v[90:91], v[98:99]

.LBB0_217:
	s_or_b64 exec, exec, s[58:59]
	s_and_saveexec_b64 s[58:59], s[0:1]
	s_cbranch_execz .LBB0_219
	s_waitcnt lgkmcnt(0)
	v_mul_f32_e32 v94, v148, v94
	v_pk_mul_f32 v[92:93], v[148:149], v[92:93]
	v_pk_mul_f32 v[88:89], v[148:149], v[88:89]
	v_mul_f32_e32 v90, v148, v90
	v_mov_b64_e32 v[108:109], v[216:217]
	v_mov_b64_e32 v[110:111], v[218:219]
	v_mov_b64_e32 v[112:113], v[212:213]
	v_mov_b64_e32 v[114:115], v[214:215]
	v_mov_b64_e32 v[116:117], v[208:209]
	v_mov_b64_e32 v[118:119], v[210:211]
	v_mov_b64_e32 v[124:125], v[204:205]
	v_mov_b64_e32 v[126:127], v[206:207]
	v_mul_f32_e32 v82, v82, v108
	v_mul_f32_e32 v90, v90, v109
	v_mul_f32_e32 v86, v86, v116
	v_mul_f32_e32 v94, v94, v117
	v_mul_f32_e32 v117, v148, v95
	v_mov_b32_e32 v116, v87
	v_pk_mul_f32 v[116:117], v[116:117], v[118:119]
	v_mov_b32_e32 v107, v126
	v_mov_b32_e32 v126, v125
	v_mov_b32_e32 v87, v116
	v_mov_b32_e32 v95, v117
	v_mov_b32_e32 v106, v124
	v_pk_mul_f32 v[92:93], v[92:93], v[126:127]
	v_pk_add_f32 v[86:87], v[86:87], v[94:95]
	v_mul_f32_e32 v95, v148, v91
	v_mov_b32_e32 v94, v83
	v_pk_fma_f32 v[84:85], v[84:85], v[106:107], v[92:93]
	v_mov_b32_e32 v93, v114
	v_mov_b32_e32 v114, v113
	v_pk_mul_f32 v[94:95], v[94:95], v[110:111]
	v_mov_b32_e32 v92, v112
	v_pk_mul_f32 v[88:89], v[88:89], v[114:115]
	v_mov_b32_e32 v83, v94
	v_mov_b32_e32 v91, v95
	v_pk_fma_f32 v[80:81], v[80:81], v[92:93], v[88:89]
	v_pk_add_f32 v[82:83], v[82:83], v[90:91]

.LBB0_227:
	s_or_b64 exec, exec, s[10:11]
	v_bitop3_b32 v88, v104, s28, 16 bitop3:0xc8
	v_cmp_lt_i32_e32 vcc, s94, v104
	v_cmp_gt_i32_e64 s[10:11], s93, v104
	s_nop 0
	v_cndmask_b32_e32 v88, v88, v146, vcc
	v_lshlrev_b32_e32 v144, 6, v88
	v_lshl_add_u64 v[88:89], s[40:41], 0, v[144:145]
	s_and_saveexec_b64 s[58:59], s[52:53]
	s_cbranch_execz .LBB0_229
	global_load_dwordx4 v[216:219], v[184:185], off offset:48
	global_load_dwordx4 v[212:215], v[184:185], off offset:32
	global_load_dwordx4 v[208:211], v[184:185], off offset:16
	global_load_dwordx4 v[204:207], v[184:185], off
	s_waitcnt lgkmcnt(0)
	v_mul_f32_e32 v86, v148, v86
	v_pk_mul_f32 v[84:85], v[148:149], v[84:85]
	v_pk_mul_f32 v[80:81], v[148:149], v[80:81]
	v_mul_f32_e32 v82, v148, v82
	s_cmp_eq_u32 s98, 0
	s_cbranch_scc1 .Lrp1_q3
	s_waitcnt vmcnt(10)
	s_branch .Lrp1_j3

.Lrp1_j3:
	v_mov_b64_e32 v[90:91], v[236:237]
	v_mov_b64_e32 v[92:93], v[238:239]
	v_mov_b64_e32 v[94:95], v[232:233]
	v_mov_b64_e32 v[96:97], v[234:235]
	v_mov_b64_e32 v[98:99], v[224:225]
	v_mov_b64_e32 v[100:101], v[226:227]
	v_mov_b64_e32 v[106:107], v[220:221]
	v_mov_b64_e32 v[108:109], v[222:223]
	v_mul_f32_e32 v74, v74, v90
	v_mul_f32_e32 v82, v82, v91
	v_mul_f32_e32 v78, v78, v98
	v_mul_f32_e32 v86, v86, v99
	v_mul_f32_e32 v99, v148, v87
	v_mov_b32_e32 v98, v79
	v_pk_mul_f32 v[98:99], v[98:99], v[100:101]
	v_mov_b32_e32 v103, v108
	v_mov_b32_e32 v108, v107
	v_mov_b32_e32 v79, v98
	v_mov_b32_e32 v87, v99
	v_mov_b32_e32 v102, v106
	v_pk_mul_f32 v[84:85], v[84:85], v[108:109]
	v_pk_add_f32 v[78:79], v[78:79], v[86:87]
	v_mul_f32_e32 v87, v148, v83
	v_mov_b32_e32 v86, v75
	v_pk_fma_f32 v[76:77], v[76:77], v[102:103], v[84:85]
	v_mov_b32_e32 v85, v96
	v_mov_b32_e32 v96, v95
	v_pk_mul_f32 v[86:87], v[86:87], v[92:93]
	v_mov_b32_e32 v84, v94
	v_pk_mul_f32 v[80:81], v[80:81], v[96:97]
	v_mov_b32_e32 v75, v86
	v_mov_b32_e32 v83, v87
	v_pk_fma_f32 v[72:73], v[72:73], v[84:85], v[80:81]
	v_pk_add_f32 v[74:75], v[74:75], v[82:83]

.LBB0_237:
	s_or_b64 exec, exec, s[58:59]
	s_and_saveexec_b64 s[58:59], s[0:1]
	s_cbranch_execz .LBB0_239
	s_waitcnt lgkmcnt(0)
	v_mul_f32_e32 v78, v148, v78
	v_pk_mul_f32 v[76:77], v[148:149], v[76:77]
	v_pk_mul_f32 v[72:73], v[148:149], v[72:73]
	v_mul_f32_e32 v74, v148, v74
	v_mov_b64_e32 v[90:91], v[236:237]
	v_mov_b64_e32 v[92:93], v[238:239]
	v_mov_b64_e32 v[94:95], v[232:233]
	v_mov_b64_e32 v[96:97], v[234:235]
	v_mov_b64_e32 v[98:99], v[224:225]
	v_mov_b64_e32 v[100:101], v[226:227]
	v_mov_b64_e32 v[102:103], v[220:221]
	v_mov_b64_e32 v[104:105], v[222:223]
	v_mul_f32_e32 v66, v66, v90
	v_mul_f32_e32 v74, v74, v91
	v_mul_f32_e32 v70, v70, v98
	v_mul_f32_e32 v78, v78, v99
	v_mul_f32_e32 v99, v148, v79
	v_mov_b32_e32 v98, v71
	v_pk_mul_f32 v[98:99], v[98:99], v[100:101]
	v_mov_b32_e32 v89, v104
	v_mov_b32_e32 v104, v103
	v_mov_b32_e32 v71, v98
	v_mov_b32_e32 v79, v99
	v_mov_b32_e32 v88, v102
	v_pk_mul_f32 v[76:77], v[76:77], v[104:105]
	v_pk_add_f32 v[70:71], v[70:71], v[78:79]
	v_mul_f32_e32 v79, v148, v75
	v_mov_b32_e32 v78, v67
	v_pk_fma_f32 v[68:69], v[68:69], v[88:89], v[76:77]
	v_mov_b32_e32 v77, v96
	v_mov_b32_e32 v96, v95
	v_pk_mul_f32 v[78:79], v[78:79], v[92:93]
	v_mov_b32_e32 v76, v94
	v_pk_mul_f32 v[72:73], v[72:73], v[96:97]
	v_mov_b32_e32 v67, v78
	v_mov_b32_e32 v75, v79
	v_pk_fma_f32 v[64:65], v[64:65], v[76:77], v[72:73]
	v_pk_add_f32 v[66:67], v[66:67], v[74:75]

.LBB0_247:
	s_or_b64 exec, exec, s[10:11]
	v_add_u32_e32 v72, s43, v169
	v_and_b32_e32 v73, 0xfcf, v72
	v_cmp_lt_i32_e32 vcc, s78, v72
	v_cmp_gt_i32_e64 s[10:11], s64, v72
	s_nop 0
	v_cndmask_b32_e32 v73, v73, v146, vcc
	v_lshlrev_b32_e32 v144, 6, v73
	v_lshl_add_u64 v[74:75], s[40:41], 0, v[144:145]
	s_and_saveexec_b64 s[58:59], s[52:53]
	s_cbranch_execz .LBB0_249
	global_load_dwordx4 v[236:239], v[184:185], off offset:1072
	global_load_dwordx4 v[232:235], v[184:185], off offset:1056
	global_load_dwordx4 v[224:227], v[184:185], off offset:1040
	global_load_dwordx4 v[220:223], v[184:185], off offset:1024
	s_waitcnt lgkmcnt(0)
	v_mul_f32_e32 v70, v148, v70
	v_pk_mul_f32 v[68:69], v[148:149], v[68:69]
	v_pk_mul_f32 v[64:65], v[148:149], v[64:65]
	v_mul_f32_e32 v66, v148, v66
	s_cmp_eq_u32 s98, 0
	s_cbranch_scc1 .Lrp1_q4
	s_waitcnt vmcnt(10)
	s_branch .Lrp1_j4

.Lrp1_j4:
	v_mov_b64_e32 v[76:77], v[216:217]
	v_mov_b64_e32 v[78:79], v[218:219]
	v_mov_b64_e32 v[80:81], v[212:213]
	v_mov_b64_e32 v[82:83], v[214:215]
	v_mov_b64_e32 v[84:85], v[208:209]
	v_mov_b64_e32 v[86:87], v[210:211]
	v_mov_b64_e32 v[88:89], v[204:205]
	v_mov_b64_e32 v[90:91], v[206:207]
	v_mul_f32_e32 v58, v58, v76
	v_mul_f32_e32 v66, v66, v77
	v_mul_f32_e32 v62, v62, v84
	v_mul_f32_e32 v70, v70, v85
	v_mul_f32_e32 v85, v148, v71
	v_mov_b32_e32 v84, v63
	v_pk_mul_f32 v[84:85], v[84:85], v[86:87]
	v_mov_b32_e32 v93, v90
	v_mov_b32_e32 v90, v89
	v_mov_b32_e32 v63, v84
	v_mov_b32_e32 v71, v85
	v_mov_b32_e32 v92, v88
	v_pk_mul_f32 v[68:69], v[68:69], v[90:91]
	v_pk_add_f32 v[62:63], v[62:63], v[70:71]
	v_mul_f32_e32 v71, v148, v67
	v_mov_b32_e32 v70, v59
	v_pk_fma_f32 v[60:61], v[60:61], v[92:93], v[68:69]
	v_mov_b32_e32 v69, v82
	v_mov_b32_e32 v82, v81
	v_pk_mul_f32 v[70:71], v[70:71], v[78:79]
	v_mov_b32_e32 v68, v80
	v_pk_mul_f32 v[64:65], v[64:65], v[82:83]
	v_mov_b32_e32 v59, v70
	v_mov_b32_e32 v67, v71
	v_pk_fma_f32 v[56:57], v[56:57], v[68:69], v[64:65]
	v_pk_add_f32 v[58:59], v[58:59], v[66:67]

.LBB0_257:
	s_or_b64 exec, exec, s[58:59]
	s_and_saveexec_b64 s[58:59], s[0:1]
	s_cbranch_execz .LBB0_259
	s_waitcnt lgkmcnt(0)
	v_mul_f32_e32 v62, v148, v62
	v_pk_mul_f32 v[60:61], v[148:149], v[60:61]
	v_pk_mul_f32 v[56:57], v[148:149], v[56:57]
	v_mul_f32_e32 v58, v148, v58
	v_mov_b64_e32 v[76:77], v[216:217]
	v_mov_b64_e32 v[78:79], v[218:219]
	v_mov_b64_e32 v[80:81], v[212:213]
	v_mov_b64_e32 v[82:83], v[214:215]
	v_mov_b64_e32 v[84:85], v[208:209]
	v_mov_b64_e32 v[86:87], v[210:211]
	v_mov_b64_e32 v[88:89], v[204:205]
	v_mov_b64_e32 v[90:91], v[206:207]
	v_mul_f32_e32 v50, v50, v76
	v_mul_f32_e32 v58, v58, v77
	v_mul_f32_e32 v54, v54, v84
	v_mul_f32_e32 v62, v62, v85
	v_mul_f32_e32 v85, v148, v63
	v_mov_b32_e32 v84, v55
	v_pk_mul_f32 v[84:85], v[84:85], v[86:87]
	v_mov_b32_e32 v75, v90
	v_mov_b32_e32 v90, v89
	v_mov_b32_e32 v55, v84
	v_mov_b32_e32 v63, v85
	v_mov_b32_e32 v74, v88
	v_pk_mul_f32 v[60:61], v[60:61], v[90:91]
	v_pk_add_f32 v[54:55], v[54:55], v[62:63]
	v_mul_f32_e32 v63, v148, v59
	v_mov_b32_e32 v62, v51
	v_pk_fma_f32 v[52:53], v[52:53], v[74:75], v[60:61]
	v_mov_b32_e32 v61, v82
	v_mov_b32_e32 v82, v81
	v_pk_mul_f32 v[62:63], v[62:63], v[78:79]
	v_mov_b32_e32 v60, v80
	v_pk_mul_f32 v[56:57], v[56:57], v[82:83]
	v_mov_b32_e32 v51, v62
	v_mov_b32_e32 v59, v63
	v_pk_fma_f32 v[48:49], v[48:49], v[60:61], v[56:57]
	v_pk_add_f32 v[50:51], v[50:51], v[58:59]

.LBB0_267:
	s_or_b64 exec, exec, s[10:11]
	v_bitop3_b32 v56, v72, s95, 16 bitop3:0xc8
	v_cmp_lt_i32_e32 vcc, s94, v72
	v_cmp_gt_i32_e64 s[10:11], s93, v72
	s_nop 0
	v_cndmask_b32_e32 v56, v56, v146, vcc
	v_lshlrev_b32_e32 v144, 6, v56
	v_lshl_add_u64 v[56:57], s[40:41], 0, v[144:145]
	s_and_saveexec_b64 s[58:59], s[52:53]
	s_cbranch_execz .LBB0_269
	global_load_dwordx4 v[216:219], v[184:185], off offset:2096
	global_load_dwordx4 v[212:215], v[184:185], off offset:2080
	global_load_dwordx4 v[208:211], v[184:185], off offset:2064
	global_load_dwordx4 v[204:207], v[184:185], off offset:2048
	s_waitcnt lgkmcnt(0)
	v_mul_f32_e32 v54, v148, v54
	v_pk_mul_f32 v[52:53], v[148:149], v[52:53]
	v_pk_mul_f32 v[48:49], v[148:149], v[48:49]
	v_mul_f32_e32 v50, v148, v50
	s_cmp_eq_u32 s98, 0
	s_cbranch_scc1 .Lrp1_q5
	s_waitcnt vmcnt(10)
	s_branch .Lrp1_j5

.Lrp1_j5:
	v_mov_b64_e32 v[58:59], v[236:237]
	v_mov_b64_e32 v[60:61], v[238:239]
	v_mov_b64_e32 v[62:63], v[232:233]
	v_mov_b64_e32 v[64:65], v[234:235]
	v_mov_b64_e32 v[66:67], v[224:225]
	v_mov_b64_e32 v[68:69], v[226:227]
	v_mov_b64_e32 v[74:75], v[220:221]
	v_mov_b64_e32 v[76:77], v[222:223]
	v_mul_f32_e32 v42, v42, v58
	v_mul_f32_e32 v50, v50, v59
	v_mul_f32_e32 v46, v46, v66
	v_mul_f32_e32 v54, v54, v67
	v_mul_f32_e32 v67, v148, v55
	v_mov_b32_e32 v66, v47
	v_pk_mul_f32 v[66:67], v[66:67], v[68:69]
	v_mov_b32_e32 v71, v76
	v_mov_b32_e32 v76, v75
	v_mov_b32_e32 v47, v66
	v_mov_b32_e32 v55, v67
	v_mov_b32_e32 v70, v74
	v_pk_mul_f32 v[52:53], v[52:53], v[76:77]
	v_pk_add_f32 v[46:47], v[46:47], v[54:55]
	v_mul_f32_e32 v55, v148, v51
	v_mov_b32_e32 v54, v43
	v_pk_fma_f32 v[44:45], v[44:45], v[70:71], v[52:53]
	v_mov_b32_e32 v53, v64
	v_mov_b32_e32 v64, v63
	v_pk_mul_f32 v[54:55], v[54:55], v[60:61]
	v_mov_b32_e32 v52, v62
	v_pk_mul_f32 v[48:49], v[48:49], v[64:65]
	v_mov_b32_e32 v43, v54
	v_mov_b32_e32 v51, v55
	v_pk_fma_f32 v[40:41], v[40:41], v[52:53], v[48:49]
	v_pk_add_f32 v[42:43], v[42:43], v[50:51]

.LBB0_277:
	s_or_b64 exec, exec, s[58:59]
	s_and_saveexec_b64 s[58:59], s[0:1]
	s_cbranch_execz .LBB0_279
	s_waitcnt lgkmcnt(0)
	v_mul_f32_e32 v46, v148, v46
	v_pk_mul_f32 v[44:45], v[148:149], v[44:45]
	v_pk_mul_f32 v[40:41], v[148:149], v[40:41]
	v_mul_f32_e32 v42, v148, v42
	v_mov_b64_e32 v[58:59], v[236:237]
	v_mov_b64_e32 v[60:61], v[238:239]
	v_mov_b64_e32 v[62:63], v[232:233]
	v_mov_b64_e32 v[64:65], v[234:235]
	v_mov_b64_e32 v[66:67], v[224:225]
	v_mov_b64_e32 v[68:69], v[226:227]
	v_mov_b64_e32 v[70:71], v[220:221]
	v_mov_b64_e32 v[72:73], v[222:223]
	v_mul_f32_e32 v34, v34, v58
	v_mul_f32_e32 v42, v42, v59
	v_mul_f32_e32 v38, v38, v66
	v_mul_f32_e32 v46, v46, v67
	v_mul_f32_e32 v67, v148, v47
	v_mov_b32_e32 v66, v39
	v_pk_mul_f32 v[66:67], v[66:67], v[68:69]
	v_mov_b32_e32 v57, v72
	v_mov_b32_e32 v72, v71
	v_mov_b32_e32 v39, v66
	v_mov_b32_e32 v47, v67
	v_mov_b32_e32 v56, v70
	v_pk_mul_f32 v[44:45], v[44:45], v[72:73]
	v_pk_add_f32 v[38:39], v[38:39], v[46:47]
	v_mul_f32_e32 v47, v148, v43
	v_mov_b32_e32 v46, v35
	v_pk_fma_f32 v[36:37], v[36:37], v[56:57], v[44:45]
	v_mov_b32_e32 v45, v64
	v_mov_b32_e32 v64, v63
	v_pk_mul_f32 v[46:47], v[46:47], v[60:61]
	v_mov_b32_e32 v44, v62
	v_pk_mul_f32 v[40:41], v[40:41], v[64:65]
	v_mov_b32_e32 v35, v46
	v_mov_b32_e32 v43, v47
	v_pk_fma_f32 v[32:33], v[32:33], v[44:45], v[40:41]
	v_pk_add_f32 v[34:35], v[34:35], v[42:43]

.LBB0_287:
	s_or_b64 exec, exec, s[10:11]
	v_add_u32_e32 v40, s43, v170
	v_and_b32_e32 v41, 0xfef, v40
	v_cmp_lt_i32_e32 vcc, s78, v40
	v_cmp_gt_i32_e64 s[10:11], s64, v40
	s_nop 0
	v_cndmask_b32_e32 v41, v41, v146, vcc
	v_lshlrev_b32_e32 v144, 6, v41
	v_lshl_add_u64 v[42:43], s[40:41], 0, v[144:145]
	s_and_saveexec_b64 s[58:59], s[52:53]
	s_cbranch_execz .LBB0_289
	global_load_dwordx4 v[236:239], v[184:185], off offset:3120
	global_load_dwordx4 v[232:235], v[184:185], off offset:3104
	global_load_dwordx4 v[224:227], v[184:185], off offset:3088
	global_load_dwordx4 v[220:223], v[184:185], off offset:3072
	s_waitcnt lgkmcnt(0)
	v_mul_f32_e32 v38, v148, v38
	v_pk_mul_f32 v[36:37], v[148:149], v[36:37]
	v_pk_mul_f32 v[32:33], v[148:149], v[32:33]
	v_mul_f32_e32 v34, v148, v34
	s_cmp_eq_u32 s98, 0
	s_cbranch_scc1 .Lrp1_q6
	s_waitcnt vmcnt(10)
	s_branch .Lrp1_j6

.Lrp1_j6:
	v_mov_b64_e32 v[44:45], v[216:217]
	v_mov_b64_e32 v[46:47], v[218:219]
	v_mov_b64_e32 v[48:49], v[212:213]
	v_mov_b64_e32 v[50:51], v[214:215]
	v_mov_b64_e32 v[52:53], v[208:209]
	v_mov_b64_e32 v[54:55], v[210:211]
	v_mov_b64_e32 v[56:57], v[204:205]
	v_mov_b64_e32 v[58:59], v[206:207]
	v_mul_f32_e32 v26, v26, v44
	v_mul_f32_e32 v34, v34, v45
	v_mul_f32_e32 v30, v30, v52
	v_mul_f32_e32 v38, v38, v53
	v_mul_f32_e32 v53, v148, v39
	v_mov_b32_e32 v52, v31
	v_pk_mul_f32 v[52:53], v[52:53], v[54:55]
	v_mov_b32_e32 v61, v58
	v_mov_b32_e32 v58, v57
	v_mov_b32_e32 v31, v52
	v_mov_b32_e32 v39, v53
	v_mov_b32_e32 v60, v56
	v_pk_mul_f32 v[36:37], v[36:37], v[58:59]
	v_pk_add_f32 v[30:31], v[30:31], v[38:39]
	v_mul_f32_e32 v39, v148, v35
	v_mov_b32_e32 v38, v27
	v_pk_fma_f32 v[28:29], v[28:29], v[60:61], v[36:37]
	v_mov_b32_e32 v37, v50
	v_mov_b32_e32 v50, v49
	v_pk_mul_f32 v[38:39], v[38:39], v[46:47]
	v_mov_b32_e32 v36, v48
	v_pk_mul_f32 v[32:33], v[32:33], v[50:51]
	v_mov_b32_e32 v27, v38
	v_mov_b32_e32 v35, v39
	v_pk_fma_f32 v[24:25], v[24:25], v[36:37], v[32:33]
	v_pk_add_f32 v[26:27], v[26:27], v[34:35]

.LBB0_297:
	s_or_b64 exec, exec, s[58:59]
	s_and_saveexec_b64 s[58:59], s[0:1]
	s_cbranch_execz .LBB0_299
	s_waitcnt lgkmcnt(0)
	v_mul_f32_e32 v30, v148, v30
	v_pk_mul_f32 v[28:29], v[148:149], v[28:29]
	v_pk_mul_f32 v[24:25], v[148:149], v[24:25]
	v_mul_f32_e32 v26, v148, v26
	v_mov_b64_e32 v[44:45], v[216:217]
	v_mov_b64_e32 v[46:47], v[218:219]
	v_mov_b64_e32 v[48:49], v[212:213]
	v_mov_b64_e32 v[50:51], v[214:215]
	v_mov_b64_e32 v[52:53], v[208:209]
	v_mov_b64_e32 v[54:55], v[210:211]
	v_mov_b64_e32 v[56:57], v[204:205]
	v_mov_b64_e32 v[58:59], v[206:207]
	v_mul_f32_e32 v18, v18, v44
	v_mul_f32_e32 v26, v26, v45
	v_mul_f32_e32 v22, v22, v52
	v_mul_f32_e32 v30, v30, v53
	v_mul_f32_e32 v53, v148, v31
	v_mov_b32_e32 v52, v23
	v_pk_mul_f32 v[52:53], v[52:53], v[54:55]
	v_mov_b32_e32 v43, v58
	v_mov_b32_e32 v58, v57
	v_mov_b32_e32 v23, v52
	v_mov_b32_e32 v31, v53
	v_mov_b32_e32 v42, v56
	v_pk_mul_f32 v[28:29], v[28:29], v[58:59]
	v_pk_add_f32 v[22:23], v[22:23], v[30:31]
	v_mul_f32_e32 v31, v148, v27
	v_mov_b32_e32 v30, v19
	v_pk_fma_f32 v[20:21], v[20:21], v[42:43], v[28:29]
	v_mov_b32_e32 v29, v50
	v_mov_b32_e32 v50, v49
	v_pk_mul_f32 v[30:31], v[30:31], v[46:47]
	v_mov_b32_e32 v28, v48
	v_pk_mul_f32 v[24:25], v[24:25], v[50:51]
	v_mov_b32_e32 v19, v30
	v_mov_b32_e32 v27, v31
	v_pk_fma_f32 v[16:17], v[16:17], v[28:29], v[24:25]
	v_pk_add_f32 v[18:19], v[18:19], v[26:27]

.LBB0_307:
	s_or_b64 exec, exec, s[10:11]
	v_bitop3_b32 v24, v40, s28, 16 bitop3:0xc8
	v_cmp_lt_i32_e32 vcc, s94, v40
	v_cmp_gt_i32_e64 s[10:11], s93, v40
	s_nop 0
	v_cndmask_b32_e32 v24, v24, v146, vcc
	v_lshlrev_b32_e32 v144, 6, v24
	v_lshl_add_u64 v[24:25], s[40:41], 0, v[144:145]
	s_and_saveexec_b64 s[54:55], s[52:53]
	s_cbranch_execz .LBB0_309
	s_waitcnt lgkmcnt(0)
	v_mul_f32_e32 v22, v148, v22
	v_pk_mul_f32 v[20:21], v[148:149], v[20:21]
	v_pk_mul_f32 v[16:17], v[148:149], v[16:17]
	v_mul_f32_e32 v18, v148, v18
	s_cmp_eq_u32 s98, 0
	s_cbranch_scc1 .Lrp1_q7
	s_waitcnt vmcnt(6)
	s_branch .Lrp1_j7

.Lrp1_j7:
	v_mov_b64_e32 v[26:27], v[236:237]
	v_mov_b64_e32 v[28:29], v[238:239]
	v_mov_b64_e32 v[30:31], v[232:233]
	v_mov_b64_e32 v[32:33], v[234:235]
	v_mov_b64_e32 v[34:35], v[224:225]
	v_mov_b64_e32 v[36:37], v[226:227]
	v_mov_b64_e32 v[42:43], v[220:221]
	v_mov_b64_e32 v[44:45], v[222:223]
	v_mul_f32_e32 v10, v10, v26
	v_mul_f32_e32 v18, v18, v27
	v_mul_f32_e32 v14, v14, v34
	v_mul_f32_e32 v22, v22, v35
	v_mul_f32_e32 v35, v148, v23
	v_mov_b32_e32 v34, v15
	v_pk_mul_f32 v[34:35], v[34:35], v[36:37]
	v_mov_b32_e32 v39, v44
	v_mov_b32_e32 v44, v43
	v_mov_b32_e32 v15, v34
	v_mov_b32_e32 v23, v35
	v_mov_b32_e32 v38, v42
	v_pk_mul_f32 v[20:21], v[20:21], v[44:45]
	v_pk_add_f32 v[14:15], v[14:15], v[22:23]
	v_mul_f32_e32 v23, v148, v19
	v_mov_b32_e32 v22, v11
	v_pk_fma_f32 v[12:13], v[12:13], v[38:39], v[20:21]
	v_mov_b32_e32 v21, v32
	v_mov_b32_e32 v32, v31
	v_pk_mul_f32 v[22:23], v[22:23], v[28:29]
	v_mov_b32_e32 v20, v30
	v_pk_mul_f32 v[16:17], v[16:17], v[32:33]
	v_mov_b32_e32 v11, v22
	v_mov_b32_e32 v19, v23
	v_pk_fma_f32 v[8:9], v[8:9], v[20:21], v[16:17]
	v_pk_add_f32 v[10:11], v[10:11], v[18:19]

.LBB0_317:
	s_or_b64 exec, exec, s[52:53]
	s_and_saveexec_b64 s[52:53], s[0:1]
	s_cbranch_execz .LBB0_319
	s_waitcnt lgkmcnt(0)
	v_mul_f32_e32 v14, v148, v14
	v_pk_mul_f32 v[12:13], v[148:149], v[12:13]
	v_pk_mul_f32 v[8:9], v[148:149], v[8:9]
	v_mul_f32_e32 v10, v148, v10
	v_mov_b64_e32 v[26:27], v[236:237]
	v_mov_b64_e32 v[28:29], v[238:239]
	v_mov_b64_e32 v[30:31], v[232:233]
	v_mov_b64_e32 v[32:33], v[234:235]
	v_mov_b64_e32 v[34:35], v[224:225]
	v_mov_b64_e32 v[36:37], v[226:227]
	v_mov_b64_e32 v[38:39], v[220:221]
	v_mov_b64_e32 v[40:41], v[222:223]
	v_mul_f32_e32 v2, v2, v26
	v_mul_f32_e32 v10, v10, v27
	v_mul_f32_e32 v6, v6, v34
	v_mul_f32_e32 v14, v14, v35
	v_mul_f32_e32 v35, v148, v15
	v_mov_b32_e32 v34, v7
	v_pk_mul_f32 v[34:35], v[34:35], v[36:37]
	v_mov_b32_e32 v25, v40
	v_mov_b32_e32 v40, v39
	v_mov_b32_e32 v7, v34
	v_mov_b32_e32 v15, v35
	v_mov_b32_e32 v24, v38
	v_pk_mul_f32 v[12:13], v[12:13], v[40:41]
	v_pk_add_f32 v[6:7], v[6:7], v[14:15]
	v_mul_f32_e32 v15, v148, v11
	v_mov_b32_e32 v14, v3
	v_pk_fma_f32 v[4:5], v[4:5], v[24:25], v[12:13]
	v_mov_b32_e32 v13, v32
	v_mov_b32_e32 v32, v31
	v_pk_mul_f32 v[14:15], v[14:15], v[28:29]
	v_mov_b32_e32 v12, v30
	v_pk_mul_f32 v[8:9], v[8:9], v[32:33]
	v_mov_b32_e32 v3, v14
	v_mov_b32_e32 v11, v15
	v_pk_fma_f32 v[0:1], v[0:1], v[12:13], v[8:9]
	v_pk_add_f32 v[2:3], v[2:3], v[10:11]
